# v72 + residual epilogue row reductions use v_permlane16/32_swap lane swaps instead of 32 ds_bpermute LDS round trips per unit
# baseline (speedup 1.0000x reference)
; __device__ __forceinline__ unsigned cvt_pk_bf16(float lo, float hi) { unsigned r; asm volatile("v_cvt_pk_bf16_f32 %0, %1, %2" : "=v"(r) : "v"(lo), "v"(hi)); return r; }
; __device__ __forceinline__ stat_t stat_fix(float ss) { return (stat_t)(ss * STAT_SCALE + 0.5f); }
;     __device__ __forceinline__ void operator()(const f32x4 (&acc)[2][2][4][2], const Unit& u, int wr, int wc, int fr_, int fq_) const {
;     ...
;                 for (int bj = 0; bj < 2; ++bj) xv[ai][m][bj] = *(const u32x4*)(XB + (size_t)(row0 + ai * HALF + m * 16) * 2048 + col0 + bj * HALF);
; #pragma unroll
;         for (int ai = 0; ai < 2; ++ai)
; #pragma unroll
;             for (int m = 0; m < 4; ++m) {
;                 const int row = row0 + ai * HALF + m * 16; bf16_t* p = XB + (size_t)row * 2048 + col0; float ss = 0.f, mxl = 0.f;
; #pragma unroll
;                 for (int bj = 0; bj < 2; ++bj) {
; #pragma unroll
;                     for (int k = 0; k < 4; ++k) {
;                         const float lo = __uint_as_float(xv[ai][m][bj][k] << 16) + acc[ai][bj][m][k >> 1][(k & 1) * 2], hi = __uint_as_float(xv[ai][m][bj][k] & 0xffff0000u) + acc[ai][bj][m][k >> 1][(k & 1) * 2 + 1];
;                         const unsigned pk = cvt_pk_bf16(lo, hi); xv[ai][m][bj][k] = pk;
;                         const float rl = __uint_as_float(pk << 16), rh = __uint_as_float(pk & 0xffff0000u);
;                         ss += rl * rl + rh * rh; mxl = fmaxf(mxl, fmaxf(fabsf(rl), fabsf(rh)));
;                     }
;                     *(u32x4*)(p + bj * HALF) = xv[ai][m][bj];
;                 }
;                 ss += __shfl_xor(ss, 16); ss += __shfl_xor(ss, 32); if (fq == 0) atomicAdd(rs_next + row, stat_fix(ss));
.LBB0_178:
	v_mov_b32_e32 v98, v246
	s_lshl_b32 s4, s66, 8
	v_readlane_b32 s5, v254, 42
	s_add_i32 s4, s4, s5
	v_and_b32_e32 v206, 15, v98
	v_or_b32_e32 v226, s4, v206
	s_lshl_b32 s4, s83, 8
	v_bfe_u32 v205, v98, 4, 2
	s_or_b32 s4, s4, s36
	v_lshl_or_b32 v228, v205, 3, s4
	v_ashrrev_i32_e32 v229, 31, v228
	v_readlane_b32 s4, v252, 16
	v_lshlrev_b64 v[244:245], 1, v[228:229]
	v_readlane_b32 s5, v252, 17
	v_ashrrev_i32_e32 v227, 31, v226
	v_mov_b32_e32 v230, v246
	v_lshl_add_u64 v[98:99], s[4:5], 0, v[244:245]
	v_lshlrev_b64 v[246:247], 12, v[226:227]
	v_lshl_add_u64 v[100:101], v[98:99], 0, v[246:247]
	global_load_dwordx4 v[190:193], v[100:101], off
	global_load_dwordx4 v[186:189], v[100:101], off offset:256
	v_or_b32_e32 v224, 16, v226
	v_ashrrev_i32_e32 v225, 31, v224
	v_or_b32_e32 v222, 32, v226
	v_lshlrev_b64 v[242:243], 12, v[224:225]
	v_ashrrev_i32_e32 v223, 31, v222
	v_or_b32_e32 v220, 48, v226
	v_lshl_add_u64 v[100:101], v[98:99], 0, v[242:243]
	v_lshlrev_b64 v[240:241], 12, v[222:223]
	v_ashrrev_i32_e32 v221, 31, v220
	v_add_u32_e32 v218, 0x80, v226
	global_load_dwordx4 v[182:185], v[100:101], off
	global_load_dwordx4 v[178:181], v[100:101], off offset:256
	v_lshl_add_u64 v[100:101], v[98:99], 0, v[240:241]
	v_lshlrev_b64 v[238:239], 12, v[220:221]
	v_ashrrev_i32_e32 v219, 31, v218
	v_add_u32_e32 v216, 0x90, v226
	global_load_dwordx4 v[174:177], v[100:101], off
	global_load_dwordx4 v[170:173], v[100:101], off offset:256
	v_lshl_add_u64 v[100:101], v[98:99], 0, v[238:239]
	v_lshlrev_b64 v[236:237], 12, v[218:219]
	v_ashrrev_i32_e32 v217, 31, v216
	global_load_dwordx4 v[166:169], v[100:101], off
	global_load_dwordx4 v[162:165], v[100:101], off offset:256
	v_lshl_add_u64 v[100:101], v[98:99], 0, v[236:237]
	v_lshlrev_b64 v[234:235], 12, v[216:217]
	v_add_u32_e32 v214, 0xa0, v226
	global_load_dwordx4 v[154:157], v[100:101], off
	global_load_dwordx4 v[146:149], v[100:101], off offset:256
	v_lshl_add_u64 v[100:101], v[98:99], 0, v[234:235]
	v_ashrrev_i32_e32 v215, 31, v214
	global_load_dwordx4 v[138:141], v[100:101], off
	global_load_dwordx4 v[130:133], v[100:101], off offset:256
	v_lshlrev_b64 v[100:101], 12, v[214:215]
	v_add_u32_e32 v212, 0xb0, v226
	v_lshl_add_u64 v[100:101], v[98:99], 0, v[100:101]
	v_ashrrev_i32_e32 v213, 31, v212
	global_load_dwordx4 v[122:125], v[100:101], off
	global_load_dwordx4 v[114:117], v[100:101], off offset:256
	v_lshlrev_b64 v[100:101], 12, v[212:213]
	v_lshl_add_u64 v[98:99], v[98:99], 0, v[100:101]
	global_load_dwordx4 v[102:105], v[98:99], off
	s_nop 0
	global_load_dwordx4 v[98:101], v[98:99], off offset:256
	v_lshl_add_u64 v[246:247], s[4:5], 0, v[246:247]
	v_lshl_add_u64 v[244:245], v[246:247], 0, v[244:245]
	v_cmp_eq_u32_e64 s[6:7], 0, v205
	s_waitcnt vmcnt(0)
	v_lshlrev_b32_e32 v207, 16, v190
	v_lshlrev_b32_e32 v246, 16, v191
	v_add_f32_e32 v158, v158, v207
	v_and_b32_e32 v190, 0xffff0000, v190
	v_add_f32_e32 v160, v160, v246
	v_and_b32_e32 v191, 0xffff0000, v191
	v_add_f32_e32 v159, v159, v190
	v_cvt_pk_bf16_f32 v190, v158, v159
	v_add_f32_e32 v161, v161, v191
	v_and_b32_e32 v158, 0xffff0000, v190
	v_cvt_pk_bf16_f32 v191, v160, v161
	v_lshlrev_b32_e32 v159, 16, v190
	v_and_b32_e32 v160, 0xffff0000, v191
	v_mul_f32_e32 v207, v158, v158
	v_lshlrev_b32_e32 v161, 16, v191
	v_mul_f32_e32 v246, v160, v160
	v_fmac_f32_e32 v207, v159, v159
	v_fmac_f32_e32 v246, v161, v161
	v_add_f32_e32 v207, v207, v246
	v_lshlrev_b32_e32 v246, 16, v192
	v_add_f32_e32 v150, v150, v246
	v_and_b32_e32 v192, 0xffff0000, v192
	v_add_f32_e32 v151, v151, v192
	v_cvt_pk_bf16_f32 v192, v150, v151
	s_nop 0
	v_and_b32_e32 v150, 0xffff0000, v192
	v_lshlrev_b32_e32 v151, 16, v192
	v_mul_f32_e32 v246, v150, v150
	v_fmac_f32_e32 v246, v151, v151
	v_add_f32_e32 v207, v207, v246
	v_lshlrev_b32_e32 v246, 16, v193
	v_and_b32_e32 v193, 0xffff0000, v193
	v_add_f32_e32 v152, v152, v246
	v_add_f32_e32 v153, v153, v193
	v_cvt_pk_bf16_f32 v193, v152, v153
	global_store_dwordx4 v[244:245], v[190:193], off
	v_and_b32_e32 v152, 0xffff0000, v193
	v_lshlrev_b32_e32 v153, 16, v193
	v_lshlrev_b32_e32 v190, 16, v186
	v_add_f32_e32 v142, v142, v190
	v_and_b32_e32 v186, 0xffff0000, v186
	v_mul_f32_e32 v246, v152, v152
	v_add_f32_e32 v143, v143, v186
	v_cvt_pk_bf16_f32 v190, v142, v143
	v_fmac_f32_e32 v246, v153, v153
	v_and_b32_e32 v142, 0xffff0000, v190
	v_lshlrev_b32_e32 v143, 16, v190
	v_mul_f32_e32 v186, v142, v142
	v_add_f32_e32 v207, v207, v246
	v_fmac_f32_e32 v186, v143, v143
	v_add_f32_e32 v192, v207, v186
	v_lshlrev_b32_e32 v186, 16, v187
	v_add_f32_e32 v144, v144, v186
	v_and_b32_e32 v186, 0xffff0000, v187
	v_add_f32_e32 v145, v145, v186
	v_cvt_pk_bf16_f32 v191, v144, v145
	s_nop 0
	v_and_b32_e32 v144, 0xffff0000, v191
	v_lshlrev_b32_e32 v186, 16, v191
	v_mul_f32_e32 v145, v144, v144
	v_fmac_f32_e32 v145, v186, v186
	v_add_f32_e32 v193, v192, v145
	v_lshlrev_b32_e32 v145, 16, v188
	v_add_f32_e32 v134, v134, v145
	v_and_b32_e32 v145, 0xffff0000, v188
	v_add_f32_e32 v135, v135, v145
	v_cvt_pk_bf16_f32 v192, v134, v135
	v_lshlrev_b32_e32 v135, 16, v189
	v_and_b32_e32 v145, 0xffff0000, v192
	v_lshlrev_b32_e32 v187, 16, v192
	v_mul_f32_e32 v134, v145, v145
	v_add_f32_e32 v135, v136, v135
	v_and_b32_e32 v136, 0xffff0000, v189
	v_fmac_f32_e32 v134, v187, v187
	v_add_f32_e32 v136, v137, v136
	v_add_f32_e32 v134, v193, v134
	v_cvt_pk_bf16_f32 v193, v135, v136
	v_and_b32_e32 v188, 64, v203
	v_and_b32_e32 v136, 0xffff0000, v193
	v_lshlrev_b32_e32 v137, 16, v193
	v_mul_f32_e32 v135, v136, v136
	v_fmac_f32_e32 v135, v137, v137
	v_add_f32_e32 v134, v134, v135
	v_xor_b32_e32 v135, 16, v203
	v_add_u32_e32 v189, 64, v188
	v_cmp_lt_i32_e32 vcc, v135, v189
	global_store_dwordx4 v[244:245], v[190:193], off offset:256
	s_nop 0
	v_cndmask_b32_e32 v135, v203, v135, vcc
	v_lshlrev_b32_e32 v188, 2, v135
	v_mov_b32_e32 v135, v134
	s_nop 1
	v_permlane16_swap_b32_e32 v135, v134
	s_waitcnt lgkmcnt(0)
	v_add_f32_e32 v190, v134, v135
	v_xor_b32_e32 v134, 32, v203
	v_cmp_lt_i32_e32 vcc, v134, v189
	s_nop 1
	v_cndmask_b32_e32 v134, v203, v134, vcc
	v_lshlrev_b32_e32 v189, 2, v134
	v_mov_b32_e32 v191, v190
	s_nop 1
	v_permlane32_swap_b32_e32 v191, v190
	v_lshl_add_u64 v[134:135], v[226:227], 3, s[44:45]
	s_and_saveexec_b64 s[8:9], s[6:7]
	s_cbranch_execz .LBB0_180
	s_waitcnt lgkmcnt(0)
	v_add_f32_e32 v190, v190, v191
	s_mov_b32 s4, 0x4b800000
	v_fma_f32 v190, v190, s4, 0.5
	v_trunc_f32_e32 v190, v190
	v_mul_f32_e32 v191, 0x2f800000, v190
	v_floor_f32_e32 v191, v191
	v_fmac_f32_e32 v190, 0xcf800000, v191
	v_cvt_u32_f32_e32 v190, v190
	v_cvt_u32_f32_e32 v191, v191
	global_atomic_add_x2 v[134:135], v[190:191], off
; __device__ __forceinline__ stat_t stat_fix(float ss) { return (stat_t)(ss * STAT_SCALE + 0.5f); }
;     __device__ __forceinline__ void operator()(const f32x4 (&acc)[2][2][4][2], const Unit& u, int wr, int wc, int fr_, int fq_) const {
;     ...
;                         ss += rl * rl + rh * rh; mxl = fmaxf(mxl, fmaxf(fabsf(rl), fabsf(rh)));
;                     }
;                     *(u32x4*)(p + bj * HALF) = xv[ai][m][bj];
;                 }
;                 ss += __shfl_xor(ss, 16); ss += __shfl_xor(ss, 32); if (fq == 0) atomicAdd(rs_next + row, stat_fix(ss));
;                 if (do_q) { mxl = fmaxf(mxl, __shfl_xor(mxl, 16)); mxl = fmaxf(mxl, __shfl_xor(mxl, 32)); if (fq == 0) atomicMax(rowmax + row, __float_as_uint(mxl)); }
.LBB0_180:
	s_or_b64 exec, exec, s[8:9]
	v_cndmask_b32_e64 v190, 0, 1, s[48:49]
	v_cmp_ne_u32_e64 s[8:9], 1, v190
	s_andn2_b64 vcc, exec, s[48:49]
	v_mov_b32_e32 v244, v202
	v_mov_b32_e32 v246, v230
	v_mov_b32_e32 v202, v231
	v_mov_b32_e32 v245, v232
	s_cbranch_vccnz .LBB0_184
	v_max_f32_e64 v190, |v158|, |v158|
	s_waitcnt lgkmcnt(0)
	v_max_f32_e64 v191, |v159|, |v159|
	v_max_f32_e32 v190, v191, v190
	v_max_f32_e64 v191, |v160|, |v160|
	v_max_f32_e64 v192, |v161|, |v161|
	v_max_f32_e32 v191, v192, v191
	v_max3_f32 v190, v190, 0, v191
	v_max_f32_e64 v191, |v150|, |v150|
	v_max_f32_e64 v192, |v151|, |v151|
	v_max_f32_e32 v191, v192, v191
	v_max_f32_e64 v192, |v152|, |v152|
	v_max_f32_e64 v193, |v153|, |v153|
	v_max_f32_e32 v192, v193, v192
	v_max3_f32 v190, v190, v191, v192
	v_max_f32_e64 v191, |v142|, |v142|
	v_max_f32_e64 v192, |v143|, |v143|
	v_max_f32_e32 v191, v192, v191
	v_max_f32_e64 v192, |v144|, |v144|
	v_max_f32_e64 v193, |v186|, |v186|
	v_max_f32_e32 v192, v193, v192
	v_max3_f32 v190, v190, v191, v192
	v_max_f32_e64 v191, |v145|, |v145|
	v_max_f32_e64 v192, |v187|, |v187|
	v_max_f32_e32 v191, v192, v191
	v_max_f32_e64 v192, |v136|, |v136|
	v_max_f32_e64 v193, |v137|, |v137|
	v_max_f32_e32 v192, v193, v192
	v_max3_f32 v190, v190, v191, v192
	v_mov_b32_e32 v191, v190
	s_nop 1
	v_permlane16_swap_b32_e32 v191, v190
	s_waitcnt lgkmcnt(0)
	v_max_f32_e32 v191, v191, v191
	v_max_f32_e32 v190, v190, v191
	v_mov_b32_e32 v191, v190
	s_nop 1
	v_permlane32_swap_b32_e32 v191, v190
	s_and_saveexec_b64 vcc, s[6:7]
	s_cbranch_execz .LBB0_183
	s_waitcnt lgkmcnt(0)
	v_max_f32_e32 v191, v191, v191
	v_max_f32_e32 v190, v190, v190
	v_max_f32_e32 v192, v190, v191
	v_lshl_add_u64 v[190:191], v[226:227], 2, s[50:51]
	global_atomic_umax v[190:191], v192, off

; __device__ __forceinline__ unsigned cvt_pk_bf16(float lo, float hi) { unsigned r; asm volatile("v_cvt_pk_bf16_f32 %0, %1, %2" : "=v"(r) : "v"(lo), "v"(hi)); return r; }
; __device__ __forceinline__ stat_t stat_fix(float ss) { return (stat_t)(ss * STAT_SCALE + 0.5f); }
;     __device__ __forceinline__ void operator()(const f32x4 (&acc)[2][2][4][2], const Unit& u, int wr, int wc, int fr_, int fq_) const {
;     ...
;                 const int row = row0 + ai * HALF + m * 16; bf16_t* p = XB + (size_t)row * 2048 + col0; float ss = 0.f, mxl = 0.f;
; #pragma unroll
;                 for (int bj = 0; bj < 2; ++bj) {
; #pragma unroll
;                     for (int k = 0; k < 4; ++k) {
;                         const float lo = __uint_as_float(xv[ai][m][bj][k] << 16) + acc[ai][bj][m][k >> 1][(k & 1) * 2], hi = __uint_as_float(xv[ai][m][bj][k] & 0xffff0000u) + acc[ai][bj][m][k >> 1][(k & 1) * 2 + 1];
;                         const unsigned pk = cvt_pk_bf16(lo, hi); xv[ai][m][bj][k] = pk;
;                         const float rl = __uint_as_float(pk << 16), rh = __uint_as_float(pk & 0xffff0000u);
;                         ss += rl * rl + rh * rh; mxl = fmaxf(mxl, fmaxf(fabsf(rl), fabsf(rh)));
;                     }
;                     *(u32x4*)(p + bj * HALF) = xv[ai][m][bj];
;                 }
;                 ss += __shfl_xor(ss, 16); ss += __shfl_xor(ss, 32); if (fq == 0) atomicAdd(rs_next + row, stat_fix(ss));
;                 if (do_q) { mxl = fmaxf(mxl, __shfl_xor(mxl, 16)); mxl = fmaxf(mxl, __shfl_xor(mxl, 32)); if (fq == 0) atomicMax(rowmax + row, __float_as_uint(mxl)); }
.LBB0_184:
	v_lshlrev_b32_e32 v192, 16, v182
	v_lshlrev_b32_e32 v193, 16, v183
	v_add_f32_e32 v126, v126, v192
	v_and_b32_e32 v182, 0xffff0000, v182
	v_add_f32_e32 v128, v128, v193
	v_and_b32_e32 v183, 0xffff0000, v183
	v_add_f32_e32 v127, v127, v182
	v_cvt_pk_bf16_f32 v182, v126, v127
	v_add_f32_e32 v129, v129, v183
	v_and_b32_e32 v126, 0xffff0000, v182
	v_cvt_pk_bf16_f32 v183, v128, v129
	v_lshlrev_b32_e32 v127, 16, v182
	v_and_b32_e32 v128, 0xffff0000, v183
	v_mul_f32_e32 v192, v126, v126
	v_lshlrev_b32_e32 v129, 16, v183
	v_mul_f32_e32 v193, v128, v128
	v_fmac_f32_e32 v192, v127, v127
	v_fmac_f32_e32 v193, v129, v129
	v_add_f32_e32 v192, v192, v193
	v_lshlrev_b32_e32 v193, 16, v184
	v_add_f32_e32 v118, v118, v193
	v_and_b32_e32 v184, 0xffff0000, v184
	v_readlane_b32 s4, v252, 16
	v_add_f32_e32 v119, v119, v184
	v_cvt_pk_bf16_f32 v184, v118, v119
	v_readlane_b32 s5, v252, 17
	v_and_b32_e32 v118, 0xffff0000, v184
	v_lshlrev_b32_e32 v119, 16, v184
	v_mul_f32_e32 v193, v118, v118
	s_waitcnt lgkmcnt(0)
	v_lshl_add_u64 v[190:191], s[4:5], 0, v[242:243]
	v_fmac_f32_e32 v193, v119, v119
	v_lshl_add_u64 v[190:191], v[228:229], 1, v[190:191]
	v_add_f32_e32 v192, v192, v193
	v_lshlrev_b32_e32 v193, 16, v185
	v_and_b32_e32 v185, 0xffff0000, v185
	v_add_f32_e32 v120, v120, v193
	v_add_f32_e32 v121, v121, v185
	v_cvt_pk_bf16_f32 v185, v120, v121
	global_store_dwordx4 v[190:191], v[182:185], off
	v_and_b32_e32 v120, 0xffff0000, v185
	v_lshlrev_b32_e32 v121, 16, v185
	v_lshlrev_b32_e32 v182, 16, v178
	v_add_f32_e32 v110, v110, v182
	v_and_b32_e32 v178, 0xffff0000, v178
	v_lshlrev_b32_e32 v183, 16, v179
	v_mul_f32_e32 v193, v120, v120
	v_add_f32_e32 v111, v111, v178
	v_cvt_pk_bf16_f32 v182, v110, v111
	v_add_f32_e32 v112, v112, v183
	v_and_b32_e32 v110, 0xffff0000, v182
	v_and_b32_e32 v179, 0xffff0000, v179
	v_fmac_f32_e32 v193, v121, v121
	v_lshlrev_b32_e32 v111, 16, v182
	v_mul_f32_e32 v178, v110, v110
	v_add_f32_e32 v113, v113, v179
	v_cvt_pk_bf16_f32 v183, v112, v113
	v_add_f32_e32 v192, v192, v193
	v_and_b32_e32 v112, 0xffff0000, v183
	v_fmac_f32_e32 v178, v111, v111
	v_lshlrev_b32_e32 v113, 16, v183
	v_mul_f32_e32 v179, v112, v112
	v_add_f32_e32 v178, v192, v178
	v_fmac_f32_e32 v179, v113, v113
	v_add_f32_e32 v178, v178, v179
	v_lshlrev_b32_e32 v179, 16, v180
	v_add_f32_e32 v106, v106, v179
	v_and_b32_e32 v179, 0xffff0000, v180
	v_add_f32_e32 v107, v107, v179
	v_cvt_pk_bf16_f32 v184, v106, v107
	s_nop 0
	v_and_b32_e32 v106, 0xffff0000, v184
	v_lshlrev_b32_e32 v107, 16, v184
	v_mul_f32_e32 v179, v106, v106
	v_fmac_f32_e32 v179, v107, v107
	v_add_f32_e32 v178, v178, v179
	v_lshlrev_b32_e32 v179, 16, v181
	v_add_f32_e32 v108, v108, v179
	v_and_b32_e32 v179, 0xffff0000, v181
	v_add_f32_e32 v109, v109, v179
	v_cvt_pk_bf16_f32 v185, v108, v109
	global_store_dwordx4 v[190:191], v[182:185], off offset:256
	v_and_b32_e32 v108, 0xffff0000, v185
	v_lshlrev_b32_e32 v109, 16, v185
	v_mul_f32_e32 v179, v108, v108
	v_fmac_f32_e32 v179, v109, v109
	v_add_f32_e32 v178, v178, v179
	v_mov_b32_e32 v179, v178
	s_nop 1
	v_permlane16_swap_b32_e32 v179, v178
	s_waitcnt lgkmcnt(0)
	v_add_f32_e32 v178, v178, v179
	v_mov_b32_e32 v179, v178
	s_nop 1
	v_permlane32_swap_b32_e32 v179, v178
	s_and_saveexec_b64 vcc, s[6:7]
	s_cbranch_execz .LBB0_186
	s_waitcnt lgkmcnt(0)
	v_add_f32_e32 v178, v178, v179
	s_mov_b32 s4, 0x4b800000
	v_fma_f32 v178, v178, s4, 0.5
	v_trunc_f32_e32 v178, v178
	v_mul_f32_e32 v179, 0x2f800000, v178
	v_floor_f32_e32 v179, v179
	v_fmac_f32_e32 v178, 0xcf800000, v179
	v_cvt_u32_f32_e32 v178, v178
	v_cvt_u32_f32_e32 v179, v179
	global_atomic_add_x2 v[134:135], v[178:179], off offset:128
.LBB0_186:
	s_or_b64 exec, exec, vcc
	s_and_b64 vcc, exec, s[8:9]
	s_cbranch_vccnz .LBB0_190
	v_max_f32_e64 v178, |v126|, |v126|
	s_waitcnt lgkmcnt(0)
	v_max_f32_e64 v179, |v127|, |v127|
	v_max_f32_e32 v178, v179, v178
	v_max_f32_e64 v179, |v128|, |v128|
	v_max_f32_e64 v180, |v129|, |v129|
	v_max_f32_e32 v179, v180, v179
	v_max3_f32 v178, v178, 0, v179
	v_max_f32_e64 v179, |v118|, |v118|
	v_max_f32_e64 v180, |v119|, |v119|
	v_max_f32_e32 v179, v180, v179
	v_max_f32_e64 v180, |v120|, |v120|
	v_max_f32_e64 v181, |v121|, |v121|
	v_max_f32_e32 v180, v181, v180
	v_max3_f32 v178, v178, v179, v180
	v_max_f32_e64 v179, |v110|, |v110|
	v_max_f32_e64 v180, |v111|, |v111|
	v_max_f32_e32 v179, v180, v179
	v_max_f32_e64 v180, |v112|, |v112|
	v_max_f32_e64 v181, |v113|, |v113|
	v_max_f32_e32 v180, v181, v180
	v_max3_f32 v178, v178, v179, v180
	v_max_f32_e64 v179, |v106|, |v106|
	v_max_f32_e64 v180, |v107|, |v107|
	v_max_f32_e32 v179, v180, v179
	v_max_f32_e64 v180, |v108|, |v108|
	v_max_f32_e64 v181, |v109|, |v109|
	v_max_f32_e32 v180, v181, v180
	v_max3_f32 v178, v178, v179, v180
	v_mov_b32_e32 v179, v178
	s_nop 1
	v_permlane16_swap_b32_e32 v179, v178
	s_waitcnt lgkmcnt(0)
	v_max_f32_e32 v179, v179, v179
	v_max_f32_e32 v178, v178, v179
	v_mov_b32_e32 v179, v178
	s_nop 1
	v_permlane32_swap_b32_e32 v179, v178
	s_and_saveexec_b64 vcc, s[6:7]
	s_cbranch_execz .LBB0_189
	s_waitcnt lgkmcnt(0)
	v_max_f32_e32 v179, v179, v179
	v_max_f32_e32 v178, v178, v178
	v_max_f32_e32 v180, v178, v179
	v_lshl_add_u64 v[178:179], v[226:227], 2, s[50:51]
	global_atomic_umax v[178:179], v180, off offset:64

; __device__ __forceinline__ unsigned cvt_pk_bf16(float lo, float hi) { unsigned r; asm volatile("v_cvt_pk_bf16_f32 %0, %1, %2" : "=v"(r) : "v"(lo), "v"(hi)); return r; }
; __device__ __forceinline__ stat_t stat_fix(float ss) { return (stat_t)(ss * STAT_SCALE + 0.5f); }
;     __device__ __forceinline__ void operator()(const f32x4 (&acc)[2][2][4][2], const Unit& u, int wr, int wc, int fr_, int fq_) const {
;     ...
;                 const int row = row0 + ai * HALF + m * 16; bf16_t* p = XB + (size_t)row * 2048 + col0; float ss = 0.f, mxl = 0.f;
; #pragma unroll
;                 for (int bj = 0; bj < 2; ++bj) {
; #pragma unroll
;                     for (int k = 0; k < 4; ++k) {
;                         const float lo = __uint_as_float(xv[ai][m][bj][k] << 16) + acc[ai][bj][m][k >> 1][(k & 1) * 2], hi = __uint_as_float(xv[ai][m][bj][k] & 0xffff0000u) + acc[ai][bj][m][k >> 1][(k & 1) * 2 + 1];
;                         const unsigned pk = cvt_pk_bf16(lo, hi); xv[ai][m][bj][k] = pk;
;                         const float rl = __uint_as_float(pk << 16), rh = __uint_as_float(pk & 0xffff0000u);
;                         ss += rl * rl + rh * rh; mxl = fmaxf(mxl, fmaxf(fabsf(rl), fabsf(rh)));
;                     }
;                     *(u32x4*)(p + bj * HALF) = xv[ai][m][bj];
;                 }
;                 ss += __shfl_xor(ss, 16); ss += __shfl_xor(ss, 32); if (fq == 0) atomicAdd(rs_next + row, stat_fix(ss));
;                 if (do_q) { mxl = fmaxf(mxl, __shfl_xor(mxl, 16)); mxl = fmaxf(mxl, __shfl_xor(mxl, 32)); if (fq == 0) atomicMax(rowmax + row, __float_as_uint(mxl)); }
.LBB0_190:
	v_lshlrev_b32_e32 v180, 16, v174
	v_lshlrev_b32_e32 v181, 16, v175
	v_add_f32_e32 v94, v94, v180
	v_and_b32_e32 v174, 0xffff0000, v174
	v_add_f32_e32 v96, v96, v181
	v_and_b32_e32 v175, 0xffff0000, v175
	v_add_f32_e32 v95, v95, v174
	v_cvt_pk_bf16_f32 v174, v94, v95
	v_add_f32_e32 v97, v97, v175
	v_and_b32_e32 v94, 0xffff0000, v174
	v_cvt_pk_bf16_f32 v175, v96, v97
	v_lshlrev_b32_e32 v95, 16, v174
	v_and_b32_e32 v96, 0xffff0000, v175
	v_mul_f32_e32 v180, v94, v94
	v_lshlrev_b32_e32 v97, 16, v175
	v_mul_f32_e32 v181, v96, v96
	v_fmac_f32_e32 v180, v95, v95
	v_fmac_f32_e32 v181, v97, v97
	v_add_f32_e32 v180, v180, v181
	v_lshlrev_b32_e32 v181, 16, v176
	v_add_f32_e32 v90, v90, v181
	v_and_b32_e32 v176, 0xffff0000, v176
	v_readlane_b32 s4, v252, 16
	v_add_f32_e32 v91, v91, v176
	v_cvt_pk_bf16_f32 v176, v90, v91
	v_readlane_b32 s5, v252, 17
	v_and_b32_e32 v90, 0xffff0000, v176
	v_lshlrev_b32_e32 v91, 16, v176
	v_mul_f32_e32 v181, v90, v90
	s_waitcnt lgkmcnt(0)
	v_lshl_add_u64 v[178:179], s[4:5], 0, v[240:241]
	v_fmac_f32_e32 v181, v91, v91
	v_lshl_add_u64 v[178:179], v[228:229], 1, v[178:179]
	v_add_f32_e32 v180, v180, v181
	v_lshlrev_b32_e32 v181, 16, v177
	v_and_b32_e32 v177, 0xffff0000, v177
	v_add_f32_e32 v92, v92, v181
	v_add_f32_e32 v93, v93, v177
	v_cvt_pk_bf16_f32 v177, v92, v93
	global_store_dwordx4 v[178:179], v[174:177], off
	v_and_b32_e32 v92, 0xffff0000, v177
	v_lshlrev_b32_e32 v93, 16, v177
	v_lshlrev_b32_e32 v174, 16, v170
	v_add_f32_e32 v86, v86, v174
	v_and_b32_e32 v170, 0xffff0000, v170
	v_lshlrev_b32_e32 v175, 16, v171
	v_mul_f32_e32 v181, v92, v92
	v_add_f32_e32 v87, v87, v170
	v_cvt_pk_bf16_f32 v174, v86, v87
	v_add_f32_e32 v88, v88, v175
	v_and_b32_e32 v86, 0xffff0000, v174
	v_and_b32_e32 v171, 0xffff0000, v171
	v_fmac_f32_e32 v181, v93, v93
	v_lshlrev_b32_e32 v87, 16, v174
	v_mul_f32_e32 v170, v86, v86
	v_add_f32_e32 v89, v89, v171
	v_cvt_pk_bf16_f32 v175, v88, v89
	v_add_f32_e32 v180, v180, v181
	v_and_b32_e32 v88, 0xffff0000, v175
	v_fmac_f32_e32 v170, v87, v87
	v_lshlrev_b32_e32 v89, 16, v175
	v_mul_f32_e32 v171, v88, v88
	v_add_f32_e32 v170, v180, v170
	v_fmac_f32_e32 v171, v89, v89
	v_add_f32_e32 v170, v170, v171
	v_lshlrev_b32_e32 v171, 16, v172
	v_add_f32_e32 v82, v82, v171
	v_and_b32_e32 v171, 0xffff0000, v172
	v_add_f32_e32 v83, v83, v171
	v_cvt_pk_bf16_f32 v176, v82, v83
	s_nop 0
	v_and_b32_e32 v82, 0xffff0000, v176
	v_lshlrev_b32_e32 v83, 16, v176
	v_mul_f32_e32 v171, v82, v82
	v_fmac_f32_e32 v171, v83, v83
	v_add_f32_e32 v170, v170, v171
	v_lshlrev_b32_e32 v171, 16, v173
	v_add_f32_e32 v84, v84, v171
	v_and_b32_e32 v171, 0xffff0000, v173
	v_add_f32_e32 v85, v85, v171
	v_cvt_pk_bf16_f32 v177, v84, v85
	global_store_dwordx4 v[178:179], v[174:177], off offset:256
	v_and_b32_e32 v84, 0xffff0000, v177
	v_lshlrev_b32_e32 v85, 16, v177
	v_mul_f32_e32 v171, v84, v84
	v_fmac_f32_e32 v171, v85, v85
	v_add_f32_e32 v170, v170, v171
	v_mov_b32_e32 v171, v170
	s_nop 1
	v_permlane16_swap_b32_e32 v171, v170
	s_waitcnt lgkmcnt(0)
	v_add_f32_e32 v170, v170, v171
	v_mov_b32_e32 v171, v170
	s_nop 1
	v_permlane32_swap_b32_e32 v171, v170
	s_and_saveexec_b64 vcc, s[6:7]
	s_cbranch_execz .LBB0_192
	s_waitcnt lgkmcnt(0)
	v_add_f32_e32 v170, v170, v171
	s_mov_b32 s4, 0x4b800000
	v_fma_f32 v170, v170, s4, 0.5
	v_trunc_f32_e32 v170, v170
	v_mul_f32_e32 v171, 0x2f800000, v170
	v_floor_f32_e32 v171, v171
	v_fmac_f32_e32 v170, 0xcf800000, v171
	v_cvt_u32_f32_e32 v170, v170
	v_cvt_u32_f32_e32 v171, v171
	global_atomic_add_x2 v[134:135], v[170:171], off offset:256
.LBB0_192:
	s_or_b64 exec, exec, vcc
	s_and_b64 vcc, exec, s[8:9]
	s_cbranch_vccnz .LBB0_196
	v_max_f32_e64 v170, |v94|, |v94|
	s_waitcnt lgkmcnt(0)
	v_max_f32_e64 v171, |v95|, |v95|
	v_max_f32_e32 v170, v171, v170
	v_max_f32_e64 v171, |v96|, |v96|
	v_max_f32_e64 v172, |v97|, |v97|
	v_max_f32_e32 v171, v172, v171
	v_max3_f32 v170, v170, 0, v171
	v_max_f32_e64 v171, |v90|, |v90|
	v_max_f32_e64 v172, |v91|, |v91|
	v_max_f32_e32 v171, v172, v171
	v_max_f32_e64 v172, |v92|, |v92|
	v_max_f32_e64 v173, |v93|, |v93|
	v_max_f32_e32 v172, v173, v172
	v_max3_f32 v170, v170, v171, v172
	v_max_f32_e64 v171, |v86|, |v86|
	v_max_f32_e64 v172, |v87|, |v87|
	v_max_f32_e32 v171, v172, v171
	v_max_f32_e64 v172, |v88|, |v88|
	v_max_f32_e64 v173, |v89|, |v89|
	v_max_f32_e32 v172, v173, v172
	v_max3_f32 v170, v170, v171, v172
	v_max_f32_e64 v171, |v82|, |v82|
	v_max_f32_e64 v172, |v83|, |v83|
	v_max_f32_e32 v171, v172, v171
	v_max_f32_e64 v172, |v84|, |v84|
	v_max_f32_e64 v173, |v85|, |v85|
	v_max_f32_e32 v172, v173, v172
	v_max3_f32 v170, v170, v171, v172
	v_mov_b32_e32 v171, v170
	s_nop 1
	v_permlane16_swap_b32_e32 v171, v170
	s_waitcnt lgkmcnt(0)
	v_max_f32_e32 v171, v171, v171
	v_max_f32_e32 v170, v170, v171
	v_mov_b32_e32 v171, v170
	s_nop 1
	v_permlane32_swap_b32_e32 v171, v170
	s_and_saveexec_b64 vcc, s[6:7]
	s_cbranch_execz .LBB0_195
	s_waitcnt lgkmcnt(0)
	v_max_f32_e32 v171, v171, v171
	v_max_f32_e32 v170, v170, v170
	v_max_f32_e32 v172, v170, v171
	v_lshl_add_u64 v[170:171], v[226:227], 2, s[50:51]
	global_atomic_umax v[170:171], v172, off offset:128

; __device__ __forceinline__ unsigned cvt_pk_bf16(float lo, float hi) { unsigned r; asm volatile("v_cvt_pk_bf16_f32 %0, %1, %2" : "=v"(r) : "v"(lo), "v"(hi)); return r; }
; __device__ __forceinline__ stat_t stat_fix(float ss) { return (stat_t)(ss * STAT_SCALE + 0.5f); }
;     __device__ __forceinline__ void operator()(const f32x4 (&acc)[2][2][4][2], const Unit& u, int wr, int wc, int fr_, int fq_) const {
;     ...
;                 const int row = row0 + ai * HALF + m * 16; bf16_t* p = XB + (size_t)row * 2048 + col0; float ss = 0.f, mxl = 0.f;
; #pragma unroll
;                 for (int bj = 0; bj < 2; ++bj) {
; #pragma unroll
;                     for (int k = 0; k < 4; ++k) {
;                         const float lo = __uint_as_float(xv[ai][m][bj][k] << 16) + acc[ai][bj][m][k >> 1][(k & 1) * 2], hi = __uint_as_float(xv[ai][m][bj][k] & 0xffff0000u) + acc[ai][bj][m][k >> 1][(k & 1) * 2 + 1];
;                         const unsigned pk = cvt_pk_bf16(lo, hi); xv[ai][m][bj][k] = pk;
;                         const float rl = __uint_as_float(pk << 16), rh = __uint_as_float(pk & 0xffff0000u);
;                         ss += rl * rl + rh * rh; mxl = fmaxf(mxl, fmaxf(fabsf(rl), fabsf(rh)));
;                     }
;                     *(u32x4*)(p + bj * HALF) = xv[ai][m][bj];
;                 }
;                 ss += __shfl_xor(ss, 16); ss += __shfl_xor(ss, 32); if (fq == 0) atomicAdd(rs_next + row, stat_fix(ss));
;                 if (do_q) { mxl = fmaxf(mxl, __shfl_xor(mxl, 16)); mxl = fmaxf(mxl, __shfl_xor(mxl, 32)); if (fq == 0) atomicMax(rowmax + row, __float_as_uint(mxl)); }
.LBB0_196:
	v_lshlrev_b32_e32 v172, 16, v166
	v_lshlrev_b32_e32 v173, 16, v167
	v_add_f32_e32 v78, v78, v172
	v_and_b32_e32 v166, 0xffff0000, v166
	v_add_f32_e32 v80, v80, v173
	v_and_b32_e32 v167, 0xffff0000, v167
	v_add_f32_e32 v79, v79, v166
	v_cvt_pk_bf16_f32 v166, v78, v79
	v_add_f32_e32 v81, v81, v167
	v_and_b32_e32 v78, 0xffff0000, v166
	v_cvt_pk_bf16_f32 v167, v80, v81
	v_lshlrev_b32_e32 v79, 16, v166
	v_and_b32_e32 v80, 0xffff0000, v167
	v_mul_f32_e32 v172, v78, v78
	v_lshlrev_b32_e32 v81, 16, v167
	v_mul_f32_e32 v173, v80, v80
	v_fmac_f32_e32 v172, v79, v79
	v_fmac_f32_e32 v173, v81, v81
	v_add_f32_e32 v172, v172, v173
	v_lshlrev_b32_e32 v173, 16, v168
	v_add_f32_e32 v74, v74, v173
	v_and_b32_e32 v168, 0xffff0000, v168
	v_readlane_b32 s4, v252, 16
	v_add_f32_e32 v75, v75, v168
	v_cvt_pk_bf16_f32 v168, v74, v75
	v_readlane_b32 s5, v252, 17
	v_and_b32_e32 v74, 0xffff0000, v168
	v_lshlrev_b32_e32 v75, 16, v168
	v_mul_f32_e32 v173, v74, v74
	s_waitcnt lgkmcnt(0)
	v_lshl_add_u64 v[170:171], s[4:5], 0, v[238:239]
	v_fmac_f32_e32 v173, v75, v75
	v_lshl_add_u64 v[170:171], v[228:229], 1, v[170:171]
	v_add_f32_e32 v172, v172, v173
	v_lshlrev_b32_e32 v173, 16, v169
	v_and_b32_e32 v169, 0xffff0000, v169
	v_add_f32_e32 v76, v76, v173
	v_add_f32_e32 v77, v77, v169
	v_cvt_pk_bf16_f32 v169, v76, v77
	global_store_dwordx4 v[170:171], v[166:169], off
	v_and_b32_e32 v76, 0xffff0000, v169
	v_lshlrev_b32_e32 v77, 16, v169
	v_lshlrev_b32_e32 v166, 16, v162
	v_add_f32_e32 v70, v70, v166
	v_and_b32_e32 v162, 0xffff0000, v162
	v_lshlrev_b32_e32 v167, 16, v163
	v_mul_f32_e32 v173, v76, v76
	v_add_f32_e32 v71, v71, v162
	v_cvt_pk_bf16_f32 v166, v70, v71
	v_add_f32_e32 v72, v72, v167
	v_and_b32_e32 v70, 0xffff0000, v166
	v_and_b32_e32 v163, 0xffff0000, v163
	v_fmac_f32_e32 v173, v77, v77
	v_lshlrev_b32_e32 v71, 16, v166
	v_mul_f32_e32 v162, v70, v70
	v_add_f32_e32 v73, v73, v163
	v_cvt_pk_bf16_f32 v167, v72, v73
	v_add_f32_e32 v172, v172, v173
	v_and_b32_e32 v72, 0xffff0000, v167
	v_fmac_f32_e32 v162, v71, v71
	v_lshlrev_b32_e32 v73, 16, v167
	v_mul_f32_e32 v163, v72, v72
	v_add_f32_e32 v162, v172, v162
	v_fmac_f32_e32 v163, v73, v73
	v_add_f32_e32 v162, v162, v163
	v_lshlrev_b32_e32 v163, 16, v164
	v_add_f32_e32 v66, v66, v163
	v_and_b32_e32 v163, 0xffff0000, v164
	v_add_f32_e32 v67, v67, v163
	v_cvt_pk_bf16_f32 v168, v66, v67
	s_nop 0
	v_and_b32_e32 v66, 0xffff0000, v168
	v_lshlrev_b32_e32 v67, 16, v168
	v_mul_f32_e32 v163, v66, v66
	v_fmac_f32_e32 v163, v67, v67
	v_add_f32_e32 v162, v162, v163
	v_lshlrev_b32_e32 v163, 16, v165
	v_add_f32_e32 v68, v68, v163
	v_and_b32_e32 v163, 0xffff0000, v165
	v_add_f32_e32 v69, v69, v163
	v_cvt_pk_bf16_f32 v169, v68, v69
	global_store_dwordx4 v[170:171], v[166:169], off offset:256
	v_and_b32_e32 v68, 0xffff0000, v169
	v_lshlrev_b32_e32 v69, 16, v169
	v_mul_f32_e32 v163, v68, v68
	v_fmac_f32_e32 v163, v69, v69
	v_add_f32_e32 v162, v162, v163
	v_mov_b32_e32 v163, v162
	s_nop 1
	v_permlane16_swap_b32_e32 v163, v162
	s_waitcnt lgkmcnt(0)
	v_add_f32_e32 v162, v162, v163
	v_mov_b32_e32 v163, v162
	s_nop 1
	v_permlane32_swap_b32_e32 v163, v162
	s_and_saveexec_b64 vcc, s[6:7]
	s_cbranch_execz .LBB0_198
	s_waitcnt lgkmcnt(0)
	v_add_f32_e32 v162, v162, v163
	s_mov_b32 s4, 0x4b800000
	v_fma_f32 v162, v162, s4, 0.5
	v_trunc_f32_e32 v162, v162
	v_mul_f32_e32 v163, 0x2f800000, v162
	v_floor_f32_e32 v163, v163
	v_fmac_f32_e32 v162, 0xcf800000, v163
	v_cvt_u32_f32_e32 v162, v162
	v_cvt_u32_f32_e32 v163, v163
	global_atomic_add_x2 v[134:135], v[162:163], off offset:384
.LBB0_198:
	s_or_b64 exec, exec, vcc
	s_and_b64 vcc, exec, s[8:9]
	s_cbranch_vccnz .LBB0_202
	v_max_f32_e64 v162, |v78|, |v78|
	s_waitcnt lgkmcnt(0)
	v_max_f32_e64 v163, |v79|, |v79|
	v_max_f32_e32 v162, v163, v162
	v_max_f32_e64 v163, |v80|, |v80|
	v_max_f32_e64 v164, |v81|, |v81|
	v_max_f32_e32 v163, v164, v163
	v_max3_f32 v162, v162, 0, v163
	v_max_f32_e64 v163, |v74|, |v74|
	v_max_f32_e64 v164, |v75|, |v75|
	v_max_f32_e32 v163, v164, v163
	v_max_f32_e64 v164, |v76|, |v76|
	v_max_f32_e64 v165, |v77|, |v77|
	v_max_f32_e32 v164, v165, v164
	v_max3_f32 v162, v162, v163, v164
	v_max_f32_e64 v163, |v70|, |v70|
	v_max_f32_e64 v164, |v71|, |v71|
	v_max_f32_e32 v163, v164, v163
	v_max_f32_e64 v164, |v72|, |v72|
	v_max_f32_e64 v165, |v73|, |v73|
	v_max_f32_e32 v164, v165, v164
	v_max3_f32 v162, v162, v163, v164
	v_max_f32_e64 v163, |v66|, |v66|
	v_max_f32_e64 v164, |v67|, |v67|
	v_max_f32_e32 v163, v164, v163
	v_max_f32_e64 v164, |v68|, |v68|
	v_max_f32_e64 v165, |v69|, |v69|
	v_max_f32_e32 v164, v165, v164
	v_max3_f32 v162, v162, v163, v164
	v_mov_b32_e32 v163, v162
	s_nop 1
	v_permlane16_swap_b32_e32 v163, v162
	s_waitcnt lgkmcnt(0)
	v_max_f32_e32 v163, v163, v163
	v_max_f32_e32 v162, v162, v163
	v_mov_b32_e32 v163, v162
	s_nop 1
	v_permlane32_swap_b32_e32 v163, v162
	s_and_saveexec_b64 vcc, s[6:7]
	s_cbranch_execz .LBB0_201
	s_waitcnt lgkmcnt(0)
	v_max_f32_e32 v163, v163, v163
	v_max_f32_e32 v162, v162, v162
	v_max_f32_e32 v164, v162, v163
	v_lshl_add_u64 v[162:163], v[226:227], 2, s[50:51]
	global_atomic_umax v[162:163], v164, off offset:192

; __device__ __forceinline__ unsigned cvt_pk_bf16(float lo, float hi) { unsigned r; asm volatile("v_cvt_pk_bf16_f32 %0, %1, %2" : "=v"(r) : "v"(lo), "v"(hi)); return r; }
; __device__ __forceinline__ stat_t stat_fix(float ss) { return (stat_t)(ss * STAT_SCALE + 0.5f); }
;     __device__ __forceinline__ void operator()(const f32x4 (&acc)[2][2][4][2], const Unit& u, int wr, int wc, int fr_, int fq_) const {
;     ...
;                 const int row = row0 + ai * HALF + m * 16; bf16_t* p = XB + (size_t)row * 2048 + col0; float ss = 0.f, mxl = 0.f;
; #pragma unroll
;                 for (int bj = 0; bj < 2; ++bj) {
; #pragma unroll
;                     for (int k = 0; k < 4; ++k) {
;                         const float lo = __uint_as_float(xv[ai][m][bj][k] << 16) + acc[ai][bj][m][k >> 1][(k & 1) * 2], hi = __uint_as_float(xv[ai][m][bj][k] & 0xffff0000u) + acc[ai][bj][m][k >> 1][(k & 1) * 2 + 1];
;                         const unsigned pk = cvt_pk_bf16(lo, hi); xv[ai][m][bj][k] = pk;
;                         const float rl = __uint_as_float(pk << 16), rh = __uint_as_float(pk & 0xffff0000u);
;                         ss += rl * rl + rh * rh; mxl = fmaxf(mxl, fmaxf(fabsf(rl), fabsf(rh)));
;                     }
;                     *(u32x4*)(p + bj * HALF) = xv[ai][m][bj];
;                 }
;                 ss += __shfl_xor(ss, 16); ss += __shfl_xor(ss, 32); if (fq == 0) atomicAdd(rs_next + row, stat_fix(ss));
;                 if (do_q) { mxl = fmaxf(mxl, __shfl_xor(mxl, 16)); mxl = fmaxf(mxl, __shfl_xor(mxl, 32)); if (fq == 0) atomicMax(rowmax + row, __float_as_uint(mxl)); }
.LBB0_202:
	v_lshlrev_b32_e32 v164, 16, v154
	v_lshlrev_b32_e32 v165, 16, v155
	v_add_f32_e32 v62, v62, v164
	v_and_b32_e32 v154, 0xffff0000, v154
	v_add_f32_e32 v64, v64, v165
	v_and_b32_e32 v155, 0xffff0000, v155
	v_add_f32_e32 v63, v63, v154
	v_cvt_pk_bf16_f32 v154, v62, v63
	v_add_f32_e32 v65, v65, v155
	v_and_b32_e32 v62, 0xffff0000, v154
	v_cvt_pk_bf16_f32 v155, v64, v65
	v_lshlrev_b32_e32 v63, 16, v154
	v_and_b32_e32 v64, 0xffff0000, v155
	v_mul_f32_e32 v164, v62, v62
	v_lshlrev_b32_e32 v65, 16, v155
	v_mul_f32_e32 v165, v64, v64
	v_fmac_f32_e32 v164, v63, v63
	v_fmac_f32_e32 v165, v65, v65
	v_add_f32_e32 v164, v164, v165
	v_lshlrev_b32_e32 v165, 16, v156
	v_add_f32_e32 v58, v58, v165
	v_and_b32_e32 v156, 0xffff0000, v156
	v_readlane_b32 s4, v252, 16
	v_add_f32_e32 v59, v59, v156
	v_cvt_pk_bf16_f32 v156, v58, v59
	v_readlane_b32 s5, v252, 17
	v_and_b32_e32 v58, 0xffff0000, v156
	v_lshlrev_b32_e32 v59, 16, v156
	v_mul_f32_e32 v165, v58, v58
	s_waitcnt lgkmcnt(0)
	v_lshl_add_u64 v[162:163], s[4:5], 0, v[236:237]
	v_fmac_f32_e32 v165, v59, v59
	v_lshl_add_u64 v[162:163], v[228:229], 1, v[162:163]
	v_add_f32_e32 v164, v164, v165
	v_lshlrev_b32_e32 v165, 16, v157
	v_and_b32_e32 v157, 0xffff0000, v157
	v_add_f32_e32 v60, v60, v165
	v_add_f32_e32 v61, v61, v157
	v_cvt_pk_bf16_f32 v157, v60, v61
	global_store_dwordx4 v[162:163], v[154:157], off
	v_and_b32_e32 v60, 0xffff0000, v157
	v_lshlrev_b32_e32 v61, 16, v157
	v_lshlrev_b32_e32 v154, 16, v146
	v_add_f32_e32 v54, v54, v154
	v_and_b32_e32 v146, 0xffff0000, v146
	v_lshlrev_b32_e32 v155, 16, v147
	v_mul_f32_e32 v165, v60, v60
	v_add_f32_e32 v55, v55, v146
	v_cvt_pk_bf16_f32 v154, v54, v55
	v_add_f32_e32 v56, v56, v155
	v_and_b32_e32 v54, 0xffff0000, v154
	v_and_b32_e32 v147, 0xffff0000, v147
	v_fmac_f32_e32 v165, v61, v61
	v_lshlrev_b32_e32 v55, 16, v154
	v_mul_f32_e32 v146, v54, v54
	v_add_f32_e32 v57, v57, v147
	v_cvt_pk_bf16_f32 v155, v56, v57
	v_add_f32_e32 v164, v164, v165
	v_and_b32_e32 v56, 0xffff0000, v155
	v_fmac_f32_e32 v146, v55, v55
	v_lshlrev_b32_e32 v57, 16, v155
	v_mul_f32_e32 v147, v56, v56
	v_add_f32_e32 v146, v164, v146
	v_fmac_f32_e32 v147, v57, v57
	v_add_f32_e32 v146, v146, v147
	v_lshlrev_b32_e32 v147, 16, v148
	v_add_f32_e32 v50, v50, v147
	v_and_b32_e32 v147, 0xffff0000, v148
	v_add_f32_e32 v51, v51, v147
	v_cvt_pk_bf16_f32 v156, v50, v51
	s_nop 0
	v_and_b32_e32 v50, 0xffff0000, v156
	v_lshlrev_b32_e32 v51, 16, v156
	v_mul_f32_e32 v147, v50, v50
	v_fmac_f32_e32 v147, v51, v51
	v_add_f32_e32 v146, v146, v147
	v_lshlrev_b32_e32 v147, 16, v149
	v_add_f32_e32 v52, v52, v147
	v_and_b32_e32 v147, 0xffff0000, v149
	v_add_f32_e32 v53, v53, v147
	v_cvt_pk_bf16_f32 v157, v52, v53
	global_store_dwordx4 v[162:163], v[154:157], off offset:256
	v_and_b32_e32 v52, 0xffff0000, v157
	v_lshlrev_b32_e32 v53, 16, v157
	v_mul_f32_e32 v147, v52, v52
	v_fmac_f32_e32 v147, v53, v53
	v_add_f32_e32 v146, v146, v147
	v_mov_b32_e32 v147, v146
	s_nop 1
	v_permlane16_swap_b32_e32 v147, v146
	s_waitcnt lgkmcnt(0)
	v_add_f32_e32 v146, v146, v147
	v_mov_b32_e32 v147, v146
	s_nop 1
	v_permlane32_swap_b32_e32 v147, v146
	s_and_saveexec_b64 vcc, s[6:7]
	s_cbranch_execz .LBB0_204
	s_waitcnt lgkmcnt(0)
	v_add_f32_e32 v146, v146, v147
	s_mov_b32 s4, 0x4b800000
	v_fma_f32 v146, v146, s4, 0.5
	v_trunc_f32_e32 v146, v146
	v_mul_f32_e32 v147, 0x2f800000, v146
	v_floor_f32_e32 v147, v147
	v_fmac_f32_e32 v146, 0xcf800000, v147
	v_cvt_u32_f32_e32 v146, v146
	v_cvt_u32_f32_e32 v147, v147
	global_atomic_add_x2 v[134:135], v[146:147], off offset:1024
.LBB0_204:
	s_or_b64 exec, exec, vcc
	s_and_b64 vcc, exec, s[8:9]
	s_cbranch_vccnz .LBB0_208
	v_max_f32_e64 v146, |v62|, |v62|
	s_waitcnt lgkmcnt(0)
	v_max_f32_e64 v147, |v63|, |v63|
	v_max_f32_e32 v146, v147, v146
	v_max_f32_e64 v147, |v64|, |v64|
	v_max_f32_e64 v148, |v65|, |v65|
	v_max_f32_e32 v147, v148, v147
	v_max3_f32 v146, v146, 0, v147
	v_max_f32_e64 v147, |v58|, |v58|
	v_max_f32_e64 v148, |v59|, |v59|
	v_max_f32_e32 v147, v148, v147
	v_max_f32_e64 v148, |v60|, |v60|
	v_max_f32_e64 v149, |v61|, |v61|
	v_max_f32_e32 v148, v149, v148
	v_max3_f32 v146, v146, v147, v148
	v_max_f32_e64 v147, |v54|, |v54|
	v_max_f32_e64 v148, |v55|, |v55|
	v_max_f32_e32 v147, v148, v147
	v_max_f32_e64 v148, |v56|, |v56|
	v_max_f32_e64 v149, |v57|, |v57|
	v_max_f32_e32 v148, v149, v148
	v_max3_f32 v146, v146, v147, v148
	v_max_f32_e64 v147, |v50|, |v50|
	v_max_f32_e64 v148, |v51|, |v51|
	v_max_f32_e32 v147, v148, v147
	v_max_f32_e64 v148, |v52|, |v52|
	v_max_f32_e64 v149, |v53|, |v53|
	v_max_f32_e32 v148, v149, v148
	v_max3_f32 v146, v146, v147, v148
	v_mov_b32_e32 v147, v146
	s_nop 1
	v_permlane16_swap_b32_e32 v147, v146
	s_waitcnt lgkmcnt(0)
	v_max_f32_e32 v147, v147, v147
	v_max_f32_e32 v146, v146, v147
	v_mov_b32_e32 v147, v146
	s_nop 1
	v_permlane32_swap_b32_e32 v147, v146
	s_and_saveexec_b64 vcc, s[6:7]
	s_cbranch_execz .LBB0_207
	s_waitcnt lgkmcnt(0)
	v_max_f32_e32 v147, v147, v147
	v_max_f32_e32 v146, v146, v146
	v_max_f32_e32 v148, v146, v147
	v_lshl_add_u64 v[146:147], v[226:227], 2, s[50:51]
	global_atomic_umax v[146:147], v148, off offset:512

; __device__ __forceinline__ unsigned cvt_pk_bf16(float lo, float hi) { unsigned r; asm volatile("v_cvt_pk_bf16_f32 %0, %1, %2" : "=v"(r) : "v"(lo), "v"(hi)); return r; }
; __device__ __forceinline__ stat_t stat_fix(float ss) { return (stat_t)(ss * STAT_SCALE + 0.5f); }
;     __device__ __forceinline__ void operator()(const f32x4 (&acc)[2][2][4][2], const Unit& u, int wr, int wc, int fr_, int fq_) const {
;     ...
;                 const int row = row0 + ai * HALF + m * 16; bf16_t* p = XB + (size_t)row * 2048 + col0; float ss = 0.f, mxl = 0.f;
; #pragma unroll
;                 for (int bj = 0; bj < 2; ++bj) {
; #pragma unroll
;                     for (int k = 0; k < 4; ++k) {
;                         const float lo = __uint_as_float(xv[ai][m][bj][k] << 16) + acc[ai][bj][m][k >> 1][(k & 1) * 2], hi = __uint_as_float(xv[ai][m][bj][k] & 0xffff0000u) + acc[ai][bj][m][k >> 1][(k & 1) * 2 + 1];
;                         const unsigned pk = cvt_pk_bf16(lo, hi); xv[ai][m][bj][k] = pk;
;                         const float rl = __uint_as_float(pk << 16), rh = __uint_as_float(pk & 0xffff0000u);
;                         ss += rl * rl + rh * rh; mxl = fmaxf(mxl, fmaxf(fabsf(rl), fabsf(rh)));
;                     }
;                     *(u32x4*)(p + bj * HALF) = xv[ai][m][bj];
;                 }
;                 ss += __shfl_xor(ss, 16); ss += __shfl_xor(ss, 32); if (fq == 0) atomicAdd(rs_next + row, stat_fix(ss));
;                 if (do_q) { mxl = fmaxf(mxl, __shfl_xor(mxl, 16)); mxl = fmaxf(mxl, __shfl_xor(mxl, 32)); if (fq == 0) atomicMax(rowmax + row, __float_as_uint(mxl)); }
.LBB0_208:
	v_lshlrev_b32_e32 v148, 16, v138
	v_lshlrev_b32_e32 v149, 16, v139
	v_add_f32_e32 v46, v46, v148
	v_and_b32_e32 v138, 0xffff0000, v138
	v_add_f32_e32 v48, v48, v149
	v_and_b32_e32 v139, 0xffff0000, v139
	v_add_f32_e32 v47, v47, v138
	v_cvt_pk_bf16_f32 v138, v46, v47
	v_add_f32_e32 v49, v49, v139
	v_and_b32_e32 v46, 0xffff0000, v138
	v_cvt_pk_bf16_f32 v139, v48, v49
	v_lshlrev_b32_e32 v47, 16, v138
	v_and_b32_e32 v48, 0xffff0000, v139
	v_mul_f32_e32 v148, v46, v46
	v_lshlrev_b32_e32 v49, 16, v139
	v_mul_f32_e32 v149, v48, v48
	v_fmac_f32_e32 v148, v47, v47
	v_fmac_f32_e32 v149, v49, v49
	v_add_f32_e32 v148, v148, v149
	v_lshlrev_b32_e32 v149, 16, v140
	v_add_f32_e32 v42, v42, v149
	v_and_b32_e32 v140, 0xffff0000, v140
	v_readlane_b32 s4, v252, 16
	v_add_f32_e32 v43, v43, v140
	v_cvt_pk_bf16_f32 v140, v42, v43
	v_readlane_b32 s5, v252, 17
	v_and_b32_e32 v42, 0xffff0000, v140
	v_lshlrev_b32_e32 v43, 16, v140
	v_mul_f32_e32 v149, v42, v42
	s_waitcnt lgkmcnt(0)
	v_lshl_add_u64 v[146:147], s[4:5], 0, v[234:235]
	v_fmac_f32_e32 v149, v43, v43
	v_lshl_add_u64 v[146:147], v[228:229], 1, v[146:147]
	v_add_f32_e32 v148, v148, v149
	v_lshlrev_b32_e32 v149, 16, v141
	v_and_b32_e32 v141, 0xffff0000, v141
	v_add_f32_e32 v44, v44, v149
	v_add_f32_e32 v45, v45, v141
	v_cvt_pk_bf16_f32 v141, v44, v45
	global_store_dwordx4 v[146:147], v[138:141], off
	v_and_b32_e32 v44, 0xffff0000, v141
	v_lshlrev_b32_e32 v45, 16, v141
	v_lshlrev_b32_e32 v138, 16, v130
	v_add_f32_e32 v38, v38, v138
	v_and_b32_e32 v130, 0xffff0000, v130
	v_lshlrev_b32_e32 v139, 16, v131
	v_mul_f32_e32 v149, v44, v44
	v_add_f32_e32 v39, v39, v130
	v_cvt_pk_bf16_f32 v138, v38, v39
	v_add_f32_e32 v40, v40, v139
	v_and_b32_e32 v38, 0xffff0000, v138
	v_and_b32_e32 v131, 0xffff0000, v131
	v_fmac_f32_e32 v149, v45, v45
	v_lshlrev_b32_e32 v39, 16, v138
	v_mul_f32_e32 v130, v38, v38
	v_add_f32_e32 v41, v41, v131
	v_cvt_pk_bf16_f32 v139, v40, v41
	v_add_f32_e32 v148, v148, v149
	v_and_b32_e32 v40, 0xffff0000, v139
	v_fmac_f32_e32 v130, v39, v39
	v_lshlrev_b32_e32 v41, 16, v139
	v_mul_f32_e32 v131, v40, v40
	v_add_f32_e32 v130, v148, v130
	v_fmac_f32_e32 v131, v41, v41
	v_add_f32_e32 v130, v130, v131
	v_lshlrev_b32_e32 v131, 16, v132
	v_add_f32_e32 v34, v34, v131
	v_and_b32_e32 v131, 0xffff0000, v132
	v_add_f32_e32 v35, v35, v131
	v_cvt_pk_bf16_f32 v140, v34, v35
	s_nop 0
	v_and_b32_e32 v34, 0xffff0000, v140
	v_lshlrev_b32_e32 v35, 16, v140
	v_mul_f32_e32 v131, v34, v34
	v_fmac_f32_e32 v131, v35, v35
	v_add_f32_e32 v130, v130, v131
	v_lshlrev_b32_e32 v131, 16, v133
	v_add_f32_e32 v36, v36, v131
	v_and_b32_e32 v131, 0xffff0000, v133
	v_add_f32_e32 v37, v37, v131
	v_cvt_pk_bf16_f32 v141, v36, v37
	global_store_dwordx4 v[146:147], v[138:141], off offset:256
	v_and_b32_e32 v36, 0xffff0000, v141
	v_lshlrev_b32_e32 v37, 16, v141
	v_mul_f32_e32 v131, v36, v36
	v_fmac_f32_e32 v131, v37, v37
	v_add_f32_e32 v130, v130, v131
	v_mov_b32_e32 v131, v130
	s_nop 1
	v_permlane16_swap_b32_e32 v131, v130
	s_waitcnt lgkmcnt(0)
	v_add_f32_e32 v130, v130, v131
	v_mov_b32_e32 v131, v130
	s_nop 1
	v_permlane32_swap_b32_e32 v131, v130
	s_and_saveexec_b64 vcc, s[6:7]
	s_cbranch_execz .LBB0_210
	s_waitcnt lgkmcnt(0)
	v_add_f32_e32 v130, v130, v131
	s_mov_b32 s4, 0x4b800000
	v_fma_f32 v130, v130, s4, 0.5
	v_trunc_f32_e32 v130, v130
	v_mul_f32_e32 v131, 0x2f800000, v130
	v_floor_f32_e32 v131, v131
	v_fmac_f32_e32 v130, 0xcf800000, v131
	v_cvt_u32_f32_e32 v130, v130
	v_cvt_u32_f32_e32 v131, v131
	global_atomic_add_x2 v[134:135], v[130:131], off offset:1152
.LBB0_210:
	s_or_b64 exec, exec, vcc
	s_and_b64 vcc, exec, s[8:9]
	s_cbranch_vccnz .LBB0_214
	v_max_f32_e64 v130, |v46|, |v46|
	s_waitcnt lgkmcnt(0)
	v_max_f32_e64 v131, |v47|, |v47|
	v_max_f32_e32 v130, v131, v130
	v_max_f32_e64 v131, |v48|, |v48|
	v_max_f32_e64 v132, |v49|, |v49|
	v_max_f32_e32 v131, v132, v131
	v_max3_f32 v130, v130, 0, v131
	v_max_f32_e64 v131, |v42|, |v42|
	v_max_f32_e64 v132, |v43|, |v43|
	v_max_f32_e32 v131, v132, v131
	v_max_f32_e64 v132, |v44|, |v44|
	v_max_f32_e64 v133, |v45|, |v45|
	v_max_f32_e32 v132, v133, v132
	v_max3_f32 v130, v130, v131, v132
	v_max_f32_e64 v131, |v38|, |v38|
	v_max_f32_e64 v132, |v39|, |v39|
	v_max_f32_e32 v131, v132, v131
	v_max_f32_e64 v132, |v40|, |v40|
	v_max_f32_e64 v133, |v41|, |v41|
	v_max_f32_e32 v132, v133, v132
	v_max3_f32 v130, v130, v131, v132
	v_max_f32_e64 v131, |v34|, |v34|
	v_max_f32_e64 v132, |v35|, |v35|
	v_max_f32_e32 v131, v132, v131
	v_max_f32_e64 v132, |v36|, |v36|
	v_max_f32_e64 v133, |v37|, |v37|
	v_max_f32_e32 v132, v133, v132
	v_max3_f32 v130, v130, v131, v132
	v_mov_b32_e32 v131, v130
	s_nop 1
	v_permlane16_swap_b32_e32 v131, v130
	s_waitcnt lgkmcnt(0)
	v_max_f32_e32 v131, v131, v131
	v_max_f32_e32 v130, v130, v131
	v_mov_b32_e32 v131, v130
	s_nop 1
	v_permlane32_swap_b32_e32 v131, v130
	s_and_saveexec_b64 vcc, s[6:7]
	s_cbranch_execz .LBB0_213
	s_waitcnt lgkmcnt(0)
	v_max_f32_e32 v131, v131, v131
	v_max_f32_e32 v130, v130, v130
	v_max_f32_e32 v132, v130, v131
	v_lshl_add_u64 v[130:131], v[226:227], 2, s[50:51]
	global_atomic_umax v[130:131], v132, off offset:576

; __device__ __forceinline__ unsigned cvt_pk_bf16(float lo, float hi) { unsigned r; asm volatile("v_cvt_pk_bf16_f32 %0, %1, %2" : "=v"(r) : "v"(lo), "v"(hi)); return r; }
; __device__ __forceinline__ stat_t stat_fix(float ss) { return (stat_t)(ss * STAT_SCALE + 0.5f); }
;     __device__ __forceinline__ void operator()(const f32x4 (&acc)[2][2][4][2], const Unit& u, int wr, int wc, int fr_, int fq_) const {
;     ...
;                 const int row = row0 + ai * HALF + m * 16; bf16_t* p = XB + (size_t)row * 2048 + col0; float ss = 0.f, mxl = 0.f;
; #pragma unroll
;                 for (int bj = 0; bj < 2; ++bj) {
; #pragma unroll
;                     for (int k = 0; k < 4; ++k) {
;                         const float lo = __uint_as_float(xv[ai][m][bj][k] << 16) + acc[ai][bj][m][k >> 1][(k & 1) * 2], hi = __uint_as_float(xv[ai][m][bj][k] & 0xffff0000u) + acc[ai][bj][m][k >> 1][(k & 1) * 2 + 1];
;                         const unsigned pk = cvt_pk_bf16(lo, hi); xv[ai][m][bj][k] = pk;
;                         const float rl = __uint_as_float(pk << 16), rh = __uint_as_float(pk & 0xffff0000u);
;                         ss += rl * rl + rh * rh; mxl = fmaxf(mxl, fmaxf(fabsf(rl), fabsf(rh)));
;                     }
;                     *(u32x4*)(p + bj * HALF) = xv[ai][m][bj];
;                 }
;                 ss += __shfl_xor(ss, 16); ss += __shfl_xor(ss, 32); if (fq == 0) atomicAdd(rs_next + row, stat_fix(ss));
;                 if (do_q) { mxl = fmaxf(mxl, __shfl_xor(mxl, 16)); mxl = fmaxf(mxl, __shfl_xor(mxl, 32)); if (fq == 0) atomicMax(rowmax + row, __float_as_uint(mxl)); }
.LBB0_214:
	v_lshlrev_b32_e32 v132, 16, v122
	v_lshlrev_b32_e32 v133, 16, v123
	v_add_f32_e32 v30, v30, v132
	v_and_b32_e32 v122, 0xffff0000, v122
	v_add_f32_e32 v32, v32, v133
	v_and_b32_e32 v123, 0xffff0000, v123
	v_add_f32_e32 v31, v31, v122
	v_cvt_pk_bf16_f32 v122, v30, v31
	v_add_f32_e32 v33, v33, v123
	v_and_b32_e32 v30, 0xffff0000, v122
	v_cvt_pk_bf16_f32 v123, v32, v33
	v_lshlrev_b32_e32 v31, 16, v122
	v_and_b32_e32 v32, 0xffff0000, v123
	v_mul_f32_e32 v132, v30, v30
	v_lshlrev_b32_e32 v33, 16, v123
	v_mul_f32_e32 v133, v32, v32
	v_fmac_f32_e32 v132, v31, v31
	v_fmac_f32_e32 v133, v33, v33
	v_add_f32_e32 v132, v132, v133
	v_lshlrev_b32_e32 v133, 16, v124
	v_add_f32_e32 v26, v26, v133
	v_and_b32_e32 v124, 0xffff0000, v124
	v_readlane_b32 s4, v252, 16
	v_add_f32_e32 v27, v27, v124
	v_cvt_pk_bf16_f32 v124, v26, v27
	v_readlane_b32 s5, v252, 17
	v_and_b32_e32 v26, 0xffff0000, v124
	s_waitcnt lgkmcnt(0)
	v_lshlrev_b64 v[130:131], 12, v[214:215]
	v_lshlrev_b32_e32 v27, 16, v124
	v_mul_f32_e32 v133, v26, v26
	v_lshl_add_u64 v[130:131], s[4:5], 0, v[130:131]
	v_fmac_f32_e32 v133, v27, v27
	v_lshl_add_u64 v[130:131], v[228:229], 1, v[130:131]
	v_add_f32_e32 v132, v132, v133
	v_lshlrev_b32_e32 v133, 16, v125
	v_and_b32_e32 v125, 0xffff0000, v125
	v_add_f32_e32 v28, v28, v133
	v_add_f32_e32 v29, v29, v125
	v_cvt_pk_bf16_f32 v125, v28, v29
	global_store_dwordx4 v[130:131], v[122:125], off
	v_and_b32_e32 v28, 0xffff0000, v125
	v_lshlrev_b32_e32 v29, 16, v125
	v_lshlrev_b32_e32 v122, 16, v114
	v_add_f32_e32 v22, v22, v122
	v_and_b32_e32 v114, 0xffff0000, v114
	v_lshlrev_b32_e32 v123, 16, v115
	v_mul_f32_e32 v133, v28, v28
	v_add_f32_e32 v23, v23, v114
	v_cvt_pk_bf16_f32 v122, v22, v23
	v_add_f32_e32 v24, v24, v123
	v_and_b32_e32 v22, 0xffff0000, v122
	v_and_b32_e32 v115, 0xffff0000, v115
	v_fmac_f32_e32 v133, v29, v29
	v_lshlrev_b32_e32 v23, 16, v122
	v_mul_f32_e32 v114, v22, v22
	v_add_f32_e32 v25, v25, v115
	v_cvt_pk_bf16_f32 v123, v24, v25
	v_add_f32_e32 v132, v132, v133
	v_and_b32_e32 v24, 0xffff0000, v123
	v_fmac_f32_e32 v114, v23, v23
	v_lshlrev_b32_e32 v25, 16, v123
	v_mul_f32_e32 v115, v24, v24
	v_add_f32_e32 v114, v132, v114
	v_fmac_f32_e32 v115, v25, v25
	v_add_f32_e32 v114, v114, v115
	v_lshlrev_b32_e32 v115, 16, v116
	v_add_f32_e32 v18, v18, v115
	v_and_b32_e32 v115, 0xffff0000, v116
	v_add_f32_e32 v19, v19, v115
	v_cvt_pk_bf16_f32 v124, v18, v19
	s_nop 0
	v_and_b32_e32 v18, 0xffff0000, v124
	v_lshlrev_b32_e32 v19, 16, v124
	v_mul_f32_e32 v115, v18, v18
	v_fmac_f32_e32 v115, v19, v19
	v_add_f32_e32 v114, v114, v115
	v_lshlrev_b32_e32 v115, 16, v117
	v_add_f32_e32 v20, v20, v115
	v_and_b32_e32 v115, 0xffff0000, v117
	v_add_f32_e32 v21, v21, v115
	v_cvt_pk_bf16_f32 v125, v20, v21
	global_store_dwordx4 v[130:131], v[122:125], off offset:256
	v_and_b32_e32 v20, 0xffff0000, v125
	v_lshlrev_b32_e32 v21, 16, v125
	v_mul_f32_e32 v115, v20, v20
	v_fmac_f32_e32 v115, v21, v21
	v_add_f32_e32 v114, v114, v115
	v_mov_b32_e32 v115, v114
	s_nop 1
	v_permlane16_swap_b32_e32 v115, v114
	s_waitcnt lgkmcnt(0)
	v_add_f32_e32 v114, v114, v115
	v_mov_b32_e32 v115, v114
	s_nop 1
	v_permlane32_swap_b32_e32 v115, v114
	s_and_saveexec_b64 vcc, s[6:7]
	s_cbranch_execz .LBB0_216
	s_waitcnt lgkmcnt(0)
	v_add_f32_e32 v114, v114, v115
	s_mov_b32 s4, 0x4b800000
	v_fma_f32 v114, v114, s4, 0.5
	v_trunc_f32_e32 v114, v114
	v_mul_f32_e32 v115, 0x2f800000, v114
	v_floor_f32_e32 v115, v115
	v_fmac_f32_e32 v114, 0xcf800000, v115
	v_cvt_u32_f32_e32 v114, v114
	v_cvt_u32_f32_e32 v115, v115
	global_atomic_add_x2 v[134:135], v[114:115], off offset:1280
.LBB0_216:
	s_or_b64 exec, exec, vcc
	s_and_b64 vcc, exec, s[8:9]
	s_cbranch_vccnz .LBB0_220
	v_max_f32_e64 v114, |v30|, |v30|
	s_waitcnt lgkmcnt(0)
	v_max_f32_e64 v115, |v31|, |v31|
	v_max_f32_e32 v114, v115, v114
	v_max_f32_e64 v115, |v32|, |v32|
	v_max_f32_e64 v116, |v33|, |v33|
	v_max_f32_e32 v115, v116, v115
	v_max3_f32 v114, v114, 0, v115
	v_max_f32_e64 v115, |v26|, |v26|
	v_max_f32_e64 v116, |v27|, |v27|
	v_max_f32_e32 v115, v116, v115
	v_max_f32_e64 v116, |v28|, |v28|
	v_max_f32_e64 v117, |v29|, |v29|
	v_max_f32_e32 v116, v117, v116
	v_max3_f32 v114, v114, v115, v116
	v_max_f32_e64 v115, |v22|, |v22|
	v_max_f32_e64 v116, |v23|, |v23|
	v_max_f32_e32 v115, v116, v115
	v_max_f32_e64 v116, |v24|, |v24|
	v_max_f32_e64 v117, |v25|, |v25|
	v_max_f32_e32 v116, v117, v116
	v_max3_f32 v114, v114, v115, v116
	v_max_f32_e64 v115, |v18|, |v18|
	v_max_f32_e64 v116, |v19|, |v19|
	v_max_f32_e32 v115, v116, v115
	v_max_f32_e64 v116, |v20|, |v20|
	v_max_f32_e64 v117, |v21|, |v21|
	v_max_f32_e32 v116, v117, v116
	v_max3_f32 v114, v114, v115, v116
	v_mov_b32_e32 v115, v114
	s_nop 1
	v_permlane16_swap_b32_e32 v115, v114
	s_waitcnt lgkmcnt(0)
	v_max_f32_e32 v115, v115, v115
	v_max_f32_e32 v114, v114, v115
	v_mov_b32_e32 v115, v114
	s_nop 1
	v_permlane32_swap_b32_e32 v115, v114
	s_and_saveexec_b64 vcc, s[6:7]
	s_cbranch_execz .LBB0_219
	s_waitcnt lgkmcnt(0)
	v_max_f32_e32 v115, v115, v115
	v_max_f32_e32 v114, v114, v114
	v_max_f32_e32 v116, v114, v115
	v_lshl_add_u64 v[114:115], v[226:227], 2, s[50:51]
	global_atomic_umax v[114:115], v116, off offset:640

; __device__ __forceinline__ unsigned cvt_pk_bf16(float lo, float hi) { unsigned r; asm volatile("v_cvt_pk_bf16_f32 %0, %1, %2" : "=v"(r) : "v"(lo), "v"(hi)); return r; }
; __device__ __forceinline__ stat_t stat_fix(float ss) { return (stat_t)(ss * STAT_SCALE + 0.5f); }
;     __device__ __forceinline__ void operator()(const f32x4 (&acc)[2][2][4][2], const Unit& u, int wr, int wc, int fr_, int fq_) const {
;     ...
;                 const int row = row0 + ai * HALF + m * 16; bf16_t* p = XB + (size_t)row * 2048 + col0; float ss = 0.f, mxl = 0.f;
; #pragma unroll
;                 for (int bj = 0; bj < 2; ++bj) {
; #pragma unroll
;                     for (int k = 0; k < 4; ++k) {
;                         const float lo = __uint_as_float(xv[ai][m][bj][k] << 16) + acc[ai][bj][m][k >> 1][(k & 1) * 2], hi = __uint_as_float(xv[ai][m][bj][k] & 0xffff0000u) + acc[ai][bj][m][k >> 1][(k & 1) * 2 + 1];
;                         const unsigned pk = cvt_pk_bf16(lo, hi); xv[ai][m][bj][k] = pk;
;                         const float rl = __uint_as_float(pk << 16), rh = __uint_as_float(pk & 0xffff0000u);
;                         ss += rl * rl + rh * rh; mxl = fmaxf(mxl, fmaxf(fabsf(rl), fabsf(rh)));
;                     }
;                     *(u32x4*)(p + bj * HALF) = xv[ai][m][bj];
;                 }
;                 ss += __shfl_xor(ss, 16); ss += __shfl_xor(ss, 32); if (fq == 0) atomicAdd(rs_next + row, stat_fix(ss));
;                 if (do_q) { mxl = fmaxf(mxl, __shfl_xor(mxl, 16)); mxl = fmaxf(mxl, __shfl_xor(mxl, 32)); if (fq == 0) atomicMax(rowmax + row, __float_as_uint(mxl)); }
.LBB0_220:
	v_lshlrev_b32_e32 v116, 16, v102
	v_lshlrev_b32_e32 v117, 16, v103
	v_add_f32_e32 v14, v14, v116
	v_and_b32_e32 v102, 0xffff0000, v102
	v_add_f32_e32 v16, v16, v117
	v_and_b32_e32 v103, 0xffff0000, v103
	v_add_f32_e32 v15, v15, v102
	v_cvt_pk_bf16_f32 v102, v14, v15
	v_add_f32_e32 v17, v17, v103
	v_and_b32_e32 v14, 0xffff0000, v102
	v_cvt_pk_bf16_f32 v103, v16, v17
	v_lshlrev_b32_e32 v15, 16, v102
	v_and_b32_e32 v16, 0xffff0000, v103
	v_mul_f32_e32 v116, v14, v14
	v_lshlrev_b32_e32 v17, 16, v103
	v_mul_f32_e32 v117, v16, v16
	v_fmac_f32_e32 v116, v15, v15
	v_fmac_f32_e32 v117, v17, v17
	v_add_f32_e32 v116, v116, v117
	v_lshlrev_b32_e32 v117, 16, v104
	v_add_f32_e32 v10, v10, v117
	v_and_b32_e32 v104, 0xffff0000, v104
	v_readlane_b32 s4, v252, 16
	v_add_f32_e32 v11, v11, v104
	v_cvt_pk_bf16_f32 v104, v10, v11
	v_readlane_b32 s5, v252, 17
	v_and_b32_e32 v10, 0xffff0000, v104
	s_waitcnt lgkmcnt(0)
	v_lshlrev_b64 v[114:115], 12, v[212:213]
	v_lshlrev_b32_e32 v11, 16, v104
	v_mul_f32_e32 v117, v10, v10
	v_lshl_add_u64 v[114:115], s[4:5], 0, v[114:115]
	v_fmac_f32_e32 v117, v11, v11
	v_lshl_add_u64 v[114:115], v[228:229], 1, v[114:115]
	v_add_f32_e32 v116, v116, v117
	v_lshlrev_b32_e32 v117, 16, v105
	v_and_b32_e32 v105, 0xffff0000, v105
	v_add_f32_e32 v12, v12, v117
	v_add_f32_e32 v13, v13, v105
	v_cvt_pk_bf16_f32 v105, v12, v13
	global_store_dwordx4 v[114:115], v[102:105], off
	v_and_b32_e32 v12, 0xffff0000, v105
	v_lshlrev_b32_e32 v13, 16, v105
	v_lshlrev_b32_e32 v102, 16, v98
	v_add_f32_e32 v6, v6, v102
	v_and_b32_e32 v98, 0xffff0000, v98
	v_mul_f32_e32 v117, v12, v12
	v_add_f32_e32 v7, v7, v98
	v_cvt_pk_bf16_f32 v102, v6, v7
	v_fmac_f32_e32 v117, v13, v13
	v_and_b32_e32 v6, 0xffff0000, v102
	v_lshlrev_b32_e32 v7, 16, v102
	v_mul_f32_e32 v98, v6, v6
	v_add_f32_e32 v116, v116, v117
	v_fmac_f32_e32 v98, v7, v7
	v_add_f32_e32 v104, v116, v98
	v_lshlrev_b32_e32 v98, 16, v99
	v_add_f32_e32 v8, v8, v98
	v_and_b32_e32 v98, 0xffff0000, v99
	v_add_f32_e32 v9, v9, v98
	v_cvt_pk_bf16_f32 v103, v8, v9
	s_nop 0
	v_and_b32_e32 v8, 0xffff0000, v103
	v_lshlrev_b32_e32 v98, 16, v103
	v_mul_f32_e32 v9, v8, v8
	v_fmac_f32_e32 v9, v98, v98
	v_add_f32_e32 v105, v104, v9
	v_lshlrev_b32_e32 v9, 16, v100
	v_add_f32_e32 v2, v2, v9
	v_and_b32_e32 v9, 0xffff0000, v100
	v_add_f32_e32 v3, v3, v9
	v_cvt_pk_bf16_f32 v104, v2, v3
	v_lshlrev_b32_e32 v3, 16, v101
	v_and_b32_e32 v9, 0xffff0000, v104
	v_lshlrev_b32_e32 v99, 16, v104
	v_mul_f32_e32 v2, v9, v9
	v_fmac_f32_e32 v2, v99, v99
	v_add_f32_e32 v3, v4, v3
	v_and_b32_e32 v4, 0xffff0000, v101
	v_add_f32_e32 v2, v105, v2
	v_add_f32_e32 v4, v5, v4
	v_cvt_pk_bf16_f32 v105, v3, v4
	global_store_dwordx4 v[114:115], v[102:105], off offset:256
	v_and_b32_e32 v100, 0xffff0000, v105
	v_lshlrev_b32_e32 v101, 16, v105
	v_mul_f32_e32 v3, v100, v100
	v_fmac_f32_e32 v3, v101, v101
	v_add_f32_e32 v2, v2, v3
	v_mov_b32_e32 v3, v2
	s_nop 1
	v_permlane16_swap_b32_e32 v3, v2
	s_waitcnt lgkmcnt(0)
	v_add_f32_e32 v2, v2, v3
	v_mov_b32_e32 v3, v2
	s_nop 1
	v_permlane32_swap_b32_e32 v3, v2
	s_and_saveexec_b64 vcc, s[6:7]
	s_cbranch_execz .LBB0_222
	s_waitcnt lgkmcnt(0)
	v_add_f32_e32 v2, v2, v3
	s_mov_b32 s4, 0x4b800000
	v_fma_f32 v2, v2, s4, 0.5
	v_trunc_f32_e32 v2, v2
	v_mul_f32_e32 v3, 0x2f800000, v2
	v_floor_f32_e32 v3, v3
	v_fmac_f32_e32 v2, 0xcf800000, v3
	v_cvt_u32_f32_e32 v2, v2
	v_cvt_u32_f32_e32 v3, v3
	global_atomic_add_x2 v[134:135], v[2:3], off offset:1408
.LBB0_222:
	s_or_b64 exec, exec, vcc
	s_and_b64 vcc, exec, s[8:9]
	s_cbranch_vccnz .LBB0_249
	v_max_f32_e64 v2, |v14|, |v14|
	s_waitcnt lgkmcnt(0)
	v_max_f32_e64 v3, |v15|, |v15|
	v_max_f32_e32 v2, v3, v2
	v_max_f32_e64 v3, |v16|, |v16|
	v_max_f32_e64 v4, |v17|, |v17|
	v_max_f32_e32 v3, v4, v3
	v_max3_f32 v2, v2, 0, v3
	v_max_f32_e64 v3, |v10|, |v10|
	v_max_f32_e64 v4, |v11|, |v11|
	v_max_f32_e32 v3, v4, v3
	v_max_f32_e64 v4, |v12|, |v12|
	v_max_f32_e64 v5, |v13|, |v13|
	v_max_f32_e32 v4, v5, v4
	v_max3_f32 v2, v2, v3, v4
	v_max_f32_e64 v3, |v6|, |v6|
	v_max_f32_e64 v4, |v7|, |v7|
	v_max_f32_e32 v3, v4, v3
	v_max_f32_e64 v4, |v8|, |v8|
	v_max_f32_e64 v5, |v98|, |v98|
	v_max_f32_e32 v4, v5, v4
	v_max3_f32 v2, v2, v3, v4
	v_max_f32_e64 v3, |v9|, |v9|
	v_max_f32_e64 v4, |v99|, |v99|
	v_max_f32_e32 v3, v4, v3
	v_max_f32_e64 v4, |v100|, |v100|
	v_max_f32_e64 v5, |v101|, |v101|
	v_max_f32_e32 v4, v5, v4
	v_max3_f32 v2, v2, v3, v4
	v_mov_b32_e32 v3, v2
	s_nop 1
	v_permlane16_swap_b32_e32 v3, v2
	s_waitcnt lgkmcnt(0)
	v_max_f32_e32 v3, v3, v3
	v_max_f32_e32 v4, v2, v3
	v_mov_b32_e32 v5, v4
	s_nop 1
	v_permlane32_swap_b32_e32 v5, v4
	v_lshl_add_u64 v[2:3], v[226:227], 2, s[50:51]
	s_and_saveexec_b64 s[8:9], s[6:7]
	s_cbranch_execz .LBB0_225
	s_waitcnt lgkmcnt(0)
	v_max_f32_e32 v5, v5, v5
	v_max_f32_e32 v4, v4, v4
	v_max_f32_e32 v4, v4, v5
	global_atomic_umax v[2:3], v4, off offset:704
